# P11 S5 local scan inner loop hand-rewritten: 8 MFMAs first, then scalar v_fma scan chain with ping-pong state regs (replaces packed-f32 + movs)
# speedup vs baseline: 1.0037x; 1.0011x over previous
.LBB0_1595:
	v_add_u32_e32 v2, s1, v168
	v_ashrrev_i32_e32 v3, 31, v2
	v_add_u32_e32 v4, 16, v2
	v_lshlrev_b64 v[2:3], 11, v[2:3]
	v_ashrrev_i32_e32 v5, 31, v4
	v_lshl_add_u64 v[2:3], v[156:157], 0, v[2:3]
	v_lshlrev_b64 v[6:7], 11, v[4:5]
	global_load_dwordx4 v[2:5], v[2:3], off
	v_lshl_add_u64 v[6:7], v[156:157], 0, v[6:7]
	global_load_dwordx4 v[114:117], v[6:7], off
	s_add_i32 s1, s1, 32
	s_cmpk_eq_i32 s1, 0x80
	s_waitcnt vmcnt(1)
	v_mfma_f32_32x32x16_bf16 v[176:191], v[2:5], v[130:133], 0
	v_mfma_f32_32x32x16_bf16 v[192:207], v[2:5], v[134:137], 0
	v_mfma_f32_32x32x16_bf16 v[208:223], v[2:5], v[138:141], 0
	v_mfma_f32_32x32x16_bf16 v[224:239], v[2:5], v[142:145], 0
	s_waitcnt vmcnt(0)
	v_mfma_f32_32x32x16_bf16 v[50:65], v[114:117], v[130:133], 0
	v_mfma_f32_32x32x16_bf16 v[66:81], v[114:117], v[134:137], 0
	v_mfma_f32_32x32x16_bf16 v[82:97], v[114:117], v[138:141], 0
	v_mfma_f32_32x32x16_bf16 v[98:113], v[114:117], v[142:145], 0
	s_nop 7
	v_fma_f32 v244, -v153, v35, v176
	v_fma_f32 v245, v153, v34, v192
	v_fma_f32 v246, -v155, v119, v208
	v_fma_f32 v247, v155, v118, v224
	v_fma_f32 v240, v152, v34, v244
	v_fma_f32 v241, v152, v35, v245
	v_fma_f32 v242, v154, v118, v246
	v_fma_f32 v243, v154, v119, v247
	v_fma_f32 v244, -v153, v241, v177
	v_fma_f32 v245, v153, v240, v193
	v_fma_f32 v246, -v155, v243, v209
	v_fma_f32 v247, v155, v242, v225
	v_fma_f32 v34, v152, v240, v244
	v_fma_f32 v35, v152, v241, v245
	v_fma_f32 v118, v154, v242, v246
	v_fma_f32 v119, v154, v243, v247
	v_fma_f32 v244, -v153, v35, v178
	v_fma_f32 v245, v153, v34, v194
	v_fma_f32 v246, -v155, v119, v210
	v_fma_f32 v247, v155, v118, v226
	v_fma_f32 v240, v152, v34, v244
	v_fma_f32 v241, v152, v35, v245
	v_fma_f32 v242, v154, v118, v246
	v_fma_f32 v243, v154, v119, v247
	v_fma_f32 v244, -v153, v241, v179
	v_fma_f32 v245, v153, v240, v195
	v_fma_f32 v246, -v155, v243, v211
	v_fma_f32 v247, v155, v242, v227
	v_fma_f32 v34, v152, v240, v244
	v_fma_f32 v35, v152, v241, v245
	v_fma_f32 v118, v154, v242, v246
	v_fma_f32 v119, v154, v243, v247
	v_fma_f32 v244, -v153, v35, v180
	v_fma_f32 v245, v153, v34, v196
	v_fma_f32 v246, -v155, v119, v212
	v_fma_f32 v247, v155, v118, v228
	v_fma_f32 v240, v152, v34, v244
	v_fma_f32 v241, v152, v35, v245
	v_fma_f32 v242, v154, v118, v246
	v_fma_f32 v243, v154, v119, v247
	v_fma_f32 v244, -v153, v241, v181
	v_fma_f32 v245, v153, v240, v197
	v_fma_f32 v246, -v155, v243, v213
	v_fma_f32 v247, v155, v242, v229
	v_fma_f32 v34, v152, v240, v244
	v_fma_f32 v35, v152, v241, v245
	v_fma_f32 v118, v154, v242, v246
	v_fma_f32 v119, v154, v243, v247
	v_fma_f32 v244, -v153, v35, v182
	v_fma_f32 v245, v153, v34, v198
	v_fma_f32 v246, -v155, v119, v214
	v_fma_f32 v247, v155, v118, v230
	v_fma_f32 v240, v152, v34, v244
	v_fma_f32 v241, v152, v35, v245
	v_fma_f32 v242, v154, v118, v246
	v_fma_f32 v243, v154, v119, v247
	v_fma_f32 v244, -v153, v241, v183
	v_fma_f32 v245, v153, v240, v199
	v_fma_f32 v246, -v155, v243, v215
	v_fma_f32 v247, v155, v242, v231
	v_fma_f32 v34, v152, v240, v244
	v_fma_f32 v35, v152, v241, v245
	v_fma_f32 v118, v154, v242, v246
	v_fma_f32 v119, v154, v243, v247
	v_fma_f32 v244, -v153, v35, v184
	v_fma_f32 v245, v153, v34, v200
	v_fma_f32 v246, -v155, v119, v216
	v_fma_f32 v247, v155, v118, v232
	v_fma_f32 v240, v152, v34, v244
	v_fma_f32 v241, v152, v35, v245
	v_fma_f32 v242, v154, v118, v246
	v_fma_f32 v243, v154, v119, v247
	v_fma_f32 v244, -v153, v241, v185
	v_fma_f32 v245, v153, v240, v201
	v_fma_f32 v246, -v155, v243, v217
	v_fma_f32 v247, v155, v242, v233
	v_fma_f32 v34, v152, v240, v244
	v_fma_f32 v35, v152, v241, v245
	v_fma_f32 v118, v154, v242, v246
	v_fma_f32 v119, v154, v243, v247
	v_fma_f32 v244, -v153, v35, v186
	v_fma_f32 v245, v153, v34, v202
	v_fma_f32 v246, -v155, v119, v218
	v_fma_f32 v247, v155, v118, v234
	v_fma_f32 v240, v152, v34, v244
	v_fma_f32 v241, v152, v35, v245
	v_fma_f32 v242, v154, v118, v246
	v_fma_f32 v243, v154, v119, v247
	v_fma_f32 v244, -v153, v241, v187
	v_fma_f32 v245, v153, v240, v203
	v_fma_f32 v246, -v155, v243, v219
	v_fma_f32 v247, v155, v242, v235
	v_fma_f32 v34, v152, v240, v244
	v_fma_f32 v35, v152, v241, v245
	v_fma_f32 v118, v154, v242, v246
	v_fma_f32 v119, v154, v243, v247
	v_fma_f32 v244, -v153, v35, v188
	v_fma_f32 v245, v153, v34, v204
	v_fma_f32 v246, -v155, v119, v220
	v_fma_f32 v247, v155, v118, v236
	v_fma_f32 v240, v152, v34, v244
	v_fma_f32 v241, v152, v35, v245
	v_fma_f32 v242, v154, v118, v246
	v_fma_f32 v243, v154, v119, v247
	v_fma_f32 v244, -v153, v241, v189
	v_fma_f32 v245, v153, v240, v205
	v_fma_f32 v246, -v155, v243, v221
	v_fma_f32 v247, v155, v242, v237
	v_fma_f32 v34, v152, v240, v244
	v_fma_f32 v35, v152, v241, v245
	v_fma_f32 v118, v154, v242, v246
	v_fma_f32 v119, v154, v243, v247
	v_fma_f32 v244, -v153, v35, v190
	v_fma_f32 v245, v153, v34, v206
	v_fma_f32 v246, -v155, v119, v222
	v_fma_f32 v247, v155, v118, v238
	v_fma_f32 v240, v152, v34, v244
	v_fma_f32 v241, v152, v35, v245
	v_fma_f32 v242, v154, v118, v246
	v_fma_f32 v243, v154, v119, v247
	v_fma_f32 v244, -v153, v241, v191
	v_fma_f32 v245, v153, v240, v207
	v_fma_f32 v246, -v155, v243, v223
	v_fma_f32 v247, v155, v242, v239
	v_fma_f32 v34, v152, v240, v244
	v_fma_f32 v35, v152, v241, v245
	v_fma_f32 v118, v154, v242, v246
	v_fma_f32 v119, v154, v243, v247
	v_fma_f32 v244, -v153, v35, v50
	v_fma_f32 v245, v153, v34, v66
	v_fma_f32 v246, -v155, v119, v82
	v_fma_f32 v247, v155, v118, v98
	v_fma_f32 v240, v152, v34, v244
	v_fma_f32 v241, v152, v35, v245
	v_fma_f32 v242, v154, v118, v246
	v_fma_f32 v243, v154, v119, v247
	v_fma_f32 v244, -v153, v241, v51
	v_fma_f32 v245, v153, v240, v67
	v_fma_f32 v246, -v155, v243, v83
	v_fma_f32 v247, v155, v242, v99
	v_fma_f32 v34, v152, v240, v244
	v_fma_f32 v35, v152, v241, v245
	v_fma_f32 v118, v154, v242, v246
	v_fma_f32 v119, v154, v243, v247
	v_fma_f32 v244, -v153, v35, v52
	v_fma_f32 v245, v153, v34, v68
	v_fma_f32 v246, -v155, v119, v84
	v_fma_f32 v247, v155, v118, v100
	v_fma_f32 v240, v152, v34, v244
	v_fma_f32 v241, v152, v35, v245
	v_fma_f32 v242, v154, v118, v246
	v_fma_f32 v243, v154, v119, v247
	v_fma_f32 v244, -v153, v241, v53
	v_fma_f32 v245, v153, v240, v69
	v_fma_f32 v246, -v155, v243, v85
	v_fma_f32 v247, v155, v242, v101
	v_fma_f32 v34, v152, v240, v244
	v_fma_f32 v35, v152, v241, v245
	v_fma_f32 v118, v154, v242, v246
	v_fma_f32 v119, v154, v243, v247
	v_fma_f32 v244, -v153, v35, v54
	v_fma_f32 v245, v153, v34, v70
	v_fma_f32 v246, -v155, v119, v86
	v_fma_f32 v247, v155, v118, v102
	v_fma_f32 v240, v152, v34, v244
	v_fma_f32 v241, v152, v35, v245
	v_fma_f32 v242, v154, v118, v246
	v_fma_f32 v243, v154, v119, v247
	v_fma_f32 v244, -v153, v241, v55
	v_fma_f32 v245, v153, v240, v71
	v_fma_f32 v246, -v155, v243, v87
	v_fma_f32 v247, v155, v242, v103
	v_fma_f32 v34, v152, v240, v244
	v_fma_f32 v35, v152, v241, v245
	v_fma_f32 v118, v154, v242, v246
	v_fma_f32 v119, v154, v243, v247
	v_fma_f32 v244, -v153, v35, v56
	v_fma_f32 v245, v153, v34, v72
	v_fma_f32 v246, -v155, v119, v88
	v_fma_f32 v247, v155, v118, v104
	v_fma_f32 v240, v152, v34, v244
	v_fma_f32 v241, v152, v35, v245
	v_fma_f32 v242, v154, v118, v246
	v_fma_f32 v243, v154, v119, v247
	v_fma_f32 v244, -v153, v241, v57
	v_fma_f32 v245, v153, v240, v73
	v_fma_f32 v246, -v155, v243, v89
	v_fma_f32 v247, v155, v242, v105
	v_fma_f32 v34, v152, v240, v244
	v_fma_f32 v35, v152, v241, v245
	v_fma_f32 v118, v154, v242, v246
	v_fma_f32 v119, v154, v243, v247
	v_fma_f32 v244, -v153, v35, v58
	v_fma_f32 v245, v153, v34, v74
	v_fma_f32 v246, -v155, v119, v90
	v_fma_f32 v247, v155, v118, v106
	v_fma_f32 v240, v152, v34, v244
	v_fma_f32 v241, v152, v35, v245
	v_fma_f32 v242, v154, v118, v246
	v_fma_f32 v243, v154, v119, v247
	v_fma_f32 v244, -v153, v241, v59
	v_fma_f32 v245, v153, v240, v75
	v_fma_f32 v246, -v155, v243, v91
	v_fma_f32 v247, v155, v242, v107
	v_fma_f32 v34, v152, v240, v244
	v_fma_f32 v35, v152, v241, v245
	v_fma_f32 v118, v154, v242, v246
	v_fma_f32 v119, v154, v243, v247
	v_fma_f32 v244, -v153, v35, v60
	v_fma_f32 v245, v153, v34, v76
	v_fma_f32 v246, -v155, v119, v92
	v_fma_f32 v247, v155, v118, v108
	v_fma_f32 v240, v152, v34, v244
	v_fma_f32 v241, v152, v35, v245
	v_fma_f32 v242, v154, v118, v246
	v_fma_f32 v243, v154, v119, v247
	v_fma_f32 v244, -v153, v241, v61
	v_fma_f32 v245, v153, v240, v77
	v_fma_f32 v246, -v155, v243, v93
	v_fma_f32 v247, v155, v242, v109
	v_fma_f32 v34, v152, v240, v244
	v_fma_f32 v35, v152, v241, v245
	v_fma_f32 v118, v154, v242, v246
	v_fma_f32 v119, v154, v243, v247
	v_fma_f32 v244, -v153, v35, v62
	v_fma_f32 v245, v153, v34, v78
	v_fma_f32 v246, -v155, v119, v94
	v_fma_f32 v247, v155, v118, v110
	v_fma_f32 v240, v152, v34, v244
	v_fma_f32 v241, v152, v35, v245
	v_fma_f32 v242, v154, v118, v246
	v_fma_f32 v243, v154, v119, v247
	v_fma_f32 v244, -v153, v241, v63
	v_fma_f32 v245, v153, v240, v79
	v_fma_f32 v246, -v155, v243, v95
	v_fma_f32 v247, v155, v242, v111
	v_fma_f32 v34, v152, v240, v244
	v_fma_f32 v35, v152, v241, v245
	v_fma_f32 v118, v154, v242, v246
	v_fma_f32 v119, v154, v243, v247
	v_fma_f32 v244, -v153, v35, v64
	v_fma_f32 v245, v153, v34, v80
	v_fma_f32 v246, -v155, v119, v96
	v_fma_f32 v247, v155, v118, v112
	v_fma_f32 v240, v152, v34, v244
	v_fma_f32 v241, v152, v35, v245
	v_fma_f32 v242, v154, v118, v246
	v_fma_f32 v243, v154, v119, v247
	v_fma_f32 v244, -v153, v241, v65
	v_fma_f32 v245, v153, v240, v81
	v_fma_f32 v246, -v155, v243, v97
	v_fma_f32 v247, v155, v242, v113
	v_fma_f32 v34, v152, v240, v244
	v_fma_f32 v35, v152, v241, v245
	v_fma_f32 v118, v154, v242, v246
	v_fma_f32 v119, v154, v243, v247
	s_cbranch_scc0 .LBB0_1595
	s_nop 0
	s_nop 0
	s_nop 0
	s_nop 0
	s_nop 0
	s_nop 0
	s_nop 0
	s_nop 0
	s_nop 0
	s_nop 0
	s_nop 0
	v_lshlrev_b32_e32 v2, 7, v167
	v_or3_b32 v2, v2, v163, v166
	v_ashrrev_i32_e32 v3, 31, v2
	v_lshlrev_b64 v[2:3], 9, v[2:3]
	s_add_i32 s0, s0, s96
	v_lshl_add_u64 v[2:3], v[150:151], 0, v[2:3]
	s_cmpk_gt_i32 s0, 0x1ff
	global_store_dwordx2 v[2:3], v[34:35], off
	global_store_dwordx2 v[2:3], v[118:119], off offset:256
	s_cbranch_scc0 .LBB0_1594
